# skip L2 writeback (buffer_wbl2) in class/group barriers when the census says all participants share one XCC
# speedup vs baseline: 1.0015x; 1.0015x over previous
; __device__ __forceinline__ unsigned xb_ld(unsigned* p)              { return __hip_atomic_load(p, __ATOMIC_RELAXED, __HIP_MEMORY_SCOPE_AGENT); }
; __device__ __forceinline__ unsigned xb_add(unsigned* p, unsigned v) { return __hip_atomic_fetch_add(p, v, __ATOMIC_RELAXED, __HIP_MEMORY_SCOPE_AGENT); }
; #define XB_SPIN(cond, bar) do { unsigned _sp = 0; while (cond) { __builtin_amdgcn_s_sleep(1); \
;     if ((++_sp & 255u) == 0u) { if (xb_ld(&(bar)[XB_TMO])) break; if (_sp > XB_SPIN_CAP) { atomicAdd(&(bar)[XB_TMO], 1u); break; } } } } while (0)
; __device__ __forceinline__ void xcd_barrier(const XcdBarrier& b) {
;     ...
;         if (nloc == 0u) { xcd_barrier_complete(bar, b.x, b.G, nloc, nx); b.st[0] = nloc; b.st[1] = nx; }
;         const unsigned old = xb_add(&bar[XB_XSUB(b.x)], 1u);
;         const unsigned gen = old / nloc;
;         if (old + 1u == (gen + 1u) * nloc) {
;             __builtin_amdgcn_fence(__ATOMIC_RELEASE, "agent");
;             asm volatile("s_waitcnt vmcnt(0)" ::: "memory");
;             if (nx > 1u) {
;             const unsigned og = xb_add(&bar[XB_TOP], 1u);
;             const unsigned tg = og / nx;
;             if (og + 1u == (tg + 1u) * nx) xb_add(&bar[XB_TOPGEN], 1u);
;             else XB_SPIN(xb_ld(&bar[XB_TOPGEN]) == tg, bar);
;             }
;             __builtin_amdgcn_fence(__ATOMIC_ACQUIRE, "agent");
;             xb_add(&bar[XB_XGEN(b.x)], 1u);
.LBB0_210:
	s_andn2_saveexec_b64 s[10:11], s[10:11]
	s_cbranch_execz .LBB0_232
	s_waitcnt lgkmcnt(0)
	v_cmp_gt_u32_e32 vcc, 2, v2
	s_cbranch_vccnz .LBB0_229
	buffer_wbl2 sc1
	s_waitcnt vmcnt(0)
	s_mov_b64 s[12:13], exec
	v_mbcnt_lo_u32_b32 v1, s12, 0
	v_mbcnt_hi_u32_b32 v1, s13, v1
	v_cmp_eq_u32_e32 vcc, 0, v1
	s_and_saveexec_b64 s[10:11], vcc
	s_cbranch_execz .LBB0_214
	s_bcnt1_i32_b64 s12, s[12:13]
	v_mov_b32_e32 v3, s12
	v_readlane_b32 s12, v253, 15
	v_readlane_b32 s13, v253, 16
	s_nop 4
	global_atomic_add v3, v0, v3, s[12:13] sc0

; __device__ __forceinline__ unsigned xb_ld(unsigned* p)              { return __hip_atomic_load(p, __ATOMIC_RELAXED, __HIP_MEMORY_SCOPE_AGENT); }
; __device__ __forceinline__ unsigned xb_add(unsigned* p, unsigned v) { return __hip_atomic_fetch_add(p, v, __ATOMIC_RELAXED, __HIP_MEMORY_SCOPE_AGENT); }
; #define XB_SPIN(cond, bar) do { unsigned _sp = 0; while (cond) { __builtin_amdgcn_s_sleep(1); \
;     if ((++_sp & 255u) == 0u) { if (xb_ld(&(bar)[XB_TMO])) break; if (_sp > XB_SPIN_CAP) { atomicAdd(&(bar)[XB_TMO], 1u); break; } } } } while (0)
; __device__ __forceinline__ void xcd_barrier(const XcdBarrier& b) {
;     ...
;         if (nloc == 0u) { xcd_barrier_complete(bar, b.x, b.G, nloc, nx); b.st[0] = nloc; b.st[1] = nx; }
;         const unsigned old = xb_add(&bar[XB_XSUB(b.x)], 1u);
;         const unsigned gen = old / nloc;
;         if (old + 1u == (gen + 1u) * nloc) {
;             __builtin_amdgcn_fence(__ATOMIC_RELEASE, "agent");
;             asm volatile("s_waitcnt vmcnt(0)" ::: "memory");
;             if (nx > 1u) {
;             const unsigned og = xb_add(&bar[XB_TOP], 1u);
;             const unsigned tg = og / nx;
;             if (og + 1u == (tg + 1u) * nx) xb_add(&bar[XB_TOPGEN], 1u);
;             else XB_SPIN(xb_ld(&bar[XB_TOPGEN]) == tg, bar);
;             }
;             __builtin_amdgcn_fence(__ATOMIC_ACQUIRE, "agent");
;             xb_add(&bar[XB_XGEN(b.x)], 1u);
.LBB0_350:
	s_andn2_saveexec_b64 s[6:7], s[6:7]
	s_cbranch_execz .LBB0_372
	s_waitcnt lgkmcnt(0)
	v_cmp_gt_u32_e32 vcc, 2, v2
	s_cbranch_vccnz .LBB0_369
	buffer_wbl2 sc1
	s_waitcnt vmcnt(0)
	s_mov_b64 s[8:9], exec
	v_mbcnt_lo_u32_b32 v1, s8, 0
	v_mbcnt_hi_u32_b32 v1, s9, v1
	v_cmp_eq_u32_e32 vcc, 0, v1
	s_and_saveexec_b64 s[6:7], vcc
	s_cbranch_execz .LBB0_354
	s_bcnt1_i32_b64 s8, s[8:9]
	v_mov_b32_e32 v3, s8
	v_readlane_b32 s8, v253, 15
	v_readlane_b32 s9, v253, 16
	s_nop 4
	global_atomic_add v3, v0, v3, s[8:9] sc0

; __device__ __forceinline__ unsigned xb_ld(unsigned* p)              { return __hip_atomic_load(p, __ATOMIC_RELAXED, __HIP_MEMORY_SCOPE_AGENT); }
; __device__ __forceinline__ unsigned xb_add(unsigned* p, unsigned v) { return __hip_atomic_fetch_add(p, v, __ATOMIC_RELAXED, __HIP_MEMORY_SCOPE_AGENT); }
; #define XB_SPIN(cond, bar) do { unsigned _sp = 0; while (cond) { __builtin_amdgcn_s_sleep(1); \
;     if ((++_sp & 255u) == 0u) { if (xb_ld(&(bar)[XB_TMO])) break; if (_sp > XB_SPIN_CAP) { atomicAdd(&(bar)[XB_TMO], 1u); break; } } } } while (0)
; __device__ __forceinline__ void xcd_barrier(const XcdBarrier& b) {
;     ...
;         if (nloc == 0u) { xcd_barrier_complete(bar, b.x, b.G, nloc, nx); b.st[0] = nloc; b.st[1] = nx; }
;         const unsigned old = xb_add(&bar[XB_XSUB(b.x)], 1u);
;         const unsigned gen = old / nloc;
;         if (old + 1u == (gen + 1u) * nloc) {
;             __builtin_amdgcn_fence(__ATOMIC_RELEASE, "agent");
;             asm volatile("s_waitcnt vmcnt(0)" ::: "memory");
;             if (nx > 1u) {
;             const unsigned og = xb_add(&bar[XB_TOP], 1u);
;             const unsigned tg = og / nx;
;             if (og + 1u == (tg + 1u) * nx) xb_add(&bar[XB_TOPGEN], 1u);
;             else XB_SPIN(xb_ld(&bar[XB_TOPGEN]) == tg, bar);
;             }
;             __builtin_amdgcn_fence(__ATOMIC_ACQUIRE, "agent");
;             xb_add(&bar[XB_XGEN(b.x)], 1u);
.LBB0_427:
	s_andn2_saveexec_b64 s[8:9], s[8:9]
	s_cbranch_execz .LBB0_449
	s_waitcnt lgkmcnt(0)
	v_cmp_gt_u32_e32 vcc, 2, v2
	s_cbranch_vccnz .LBB0_446
	buffer_wbl2 sc1
	s_waitcnt vmcnt(0)
	s_mov_b64 s[10:11], exec
	v_mbcnt_lo_u32_b32 v1, s10, 0
	v_mbcnt_hi_u32_b32 v1, s11, v1
	v_cmp_eq_u32_e32 vcc, 0, v1
	s_and_saveexec_b64 s[8:9], vcc
	s_cbranch_execz .LBB0_431
	s_bcnt1_i32_b64 s10, s[10:11]
	v_mov_b32_e32 v3, s10
	v_readlane_b32 s10, v253, 37
	v_readlane_b32 s11, v253, 38
	s_nop 4
	global_atomic_add v3, v0, v3, s[10:11] sc0

; __device__ __forceinline__ unsigned xb_ld(unsigned* p)              { return __hip_atomic_load(p, __ATOMIC_RELAXED, __HIP_MEMORY_SCOPE_AGENT); }
; __device__ __forceinline__ unsigned xb_add(unsigned* p, unsigned v) { return __hip_atomic_fetch_add(p, v, __ATOMIC_RELAXED, __HIP_MEMORY_SCOPE_AGENT); }
; #define XB_SPIN(cond, bar) do { unsigned _sp = 0; while (cond) { __builtin_amdgcn_s_sleep(1); \
;     if ((++_sp & 255u) == 0u) { if (xb_ld(&(bar)[XB_TMO])) break; if (_sp > XB_SPIN_CAP) { atomicAdd(&(bar)[XB_TMO], 1u); break; } } } } while (0)
; __device__ __forceinline__ void xcd_barrier(const XcdBarrier& b) {
;     ...
;         if (nloc == 0u) { xcd_barrier_complete(bar, b.x, b.G, nloc, nx); b.st[0] = nloc; b.st[1] = nx; }
;         const unsigned old = xb_add(&bar[XB_XSUB(b.x)], 1u);
;         const unsigned gen = old / nloc;
;         if (old + 1u == (gen + 1u) * nloc) {
;             __builtin_amdgcn_fence(__ATOMIC_RELEASE, "agent");
;             asm volatile("s_waitcnt vmcnt(0)" ::: "memory");
;             if (nx > 1u) {
;             const unsigned og = xb_add(&bar[XB_TOP], 1u);
;             const unsigned tg = og / nx;
;             if (og + 1u == (tg + 1u) * nx) xb_add(&bar[XB_TOPGEN], 1u);
;             else XB_SPIN(xb_ld(&bar[XB_TOPGEN]) == tg, bar);
;             }
;             __builtin_amdgcn_fence(__ATOMIC_ACQUIRE, "agent");
;             xb_add(&bar[XB_XGEN(b.x)], 1u);
.LBB0_544:
	s_andn2_saveexec_b64 s[6:7], s[6:7]
	s_cbranch_execz .LBB0_566
	s_waitcnt lgkmcnt(0)
	v_cmp_gt_u32_e32 vcc, 2, v2
	s_cbranch_vccnz .LBB0_563
	buffer_wbl2 sc1
	s_waitcnt vmcnt(0)
	s_mov_b64 s[8:9], exec
	v_mbcnt_lo_u32_b32 v1, s8, 0
	v_mbcnt_hi_u32_b32 v1, s9, v1
	v_cmp_eq_u32_e32 vcc, 0, v1
	s_and_saveexec_b64 s[6:7], vcc
	s_cbranch_execz .LBB0_548
	s_bcnt1_i32_b64 s8, s[8:9]
	v_mov_b32_e32 v3, s8
	v_readlane_b32 s8, v253, 37
	v_readlane_b32 s9, v253, 38
	s_nop 4
	global_atomic_add v3, v0, v3, s[8:9] sc0
